# combo7 + dn_prep: touch the k/v-part z rows while the q-part loads are issued (L2 prefetch)
# baseline (speedup 1.0000x reference)
; __device__ __forceinline__ void dn_prep(const Params& p, LAS unsigned char* lds) {
;     ...
;             const int t = tid2 >> 3, sub = tid2 & 7, d0 = sub * 16;
;             const bool valid = t < ntok;
;             const bool whist = valid && (samp || n == 31) && (t >= ntok - 3);
;             float* hist_out = p.out + (samp ? O_SBC : O_PBC) + (size_t)(b * 3 + (t - (ntok - 3))) * 1536;
; #pragma unroll
;             for (int part = 0; part < 3; ++part) {
;                 bf16x8 raw[4][2];
; #pragma unroll
;                 for (int j = 0; j < 4; ++j) { const int tt = t - 3 + j; int te = (tt >= 0 || (!samp && n > 0)) ? tt : 0; te = te < ntok ? te : ntok - 1;
;                     const bf16_t* zp = Z + (size_t)(row0 + te) * NZ + ZC_BQKV + part * 512 + h * 128 + d0;
;                     raw[j][0] = *(const bf16x8*)zp; raw[j][1] = *(const bf16x8*)(zp + 8); }
.LBB0_205:
	s_or_b64 exec, exec, s[24:25]
	v_mov_b32 v0, 0
	s_cmp_eq_u32 s16, 0
	v_add_u32_e32 v235, v0, v184
	v_ashrrev_i32_e32 v232, 3, v235
	s_cselect_b64 s[0:1], -1, 0
	v_add_u32_e32 v2, -2, v232
	s_or_b64 s[26:27], s[68:69], s[0:1]
	v_max_i32_e32 v3, 0, v2
	v_add_u32_e32 v0, -3, v232
	s_add_i32 s18, s6, -1
	v_cndmask_b32_e64 v2, v2, v3, s[26:27]
	v_max_i32_e32 v1, 0, v0
	v_min_i32_e32 v2, s18, v2
	v_cndmask_b32_e64 v6, v0, v1, s[26:27]
	v_mov_b64_e32 v[0:1], s[50:51]
	v_add_u32_e32 v2, s90, v2
	v_and_b32_e32 v139, 7, v235
	v_mad_i64_i32 v[130:131], s[0:1], v2, s38, v[0:1]
	s_lshl_b32 s40, s17, 8
	v_lshl_add_u64 v[2:3], v[130:131], 0, s[40:41]
	v_lshlrev_b32_e32 v132, 5, v139
	v_lshl_add_u64 v[2:3], v[2:3], 0, v[132:133]
	v_lshl_add_u64 v[4:5], v[2:3], 0, s[42:43]
	v_add_co_u32_e32 v2, vcc, s8, v2
	v_lshlrev_b32_e32 v234, 4, v139
	s_nop 0
	v_addc_co_u32_e32 v3, vcc, 0, v3, vcc
	global_load_dwordx4 v[60:63], v[2:3], off offset:2560
	global_load_dwordx4 v[56:59], v[4:5], off offset:16
	global_load_dword v176, v[4:5], off offset:1040
	global_load_dword v177, v[4:5], off offset:2064
	v_add_u32_e32 v2, -1, v232
	v_max_i32_e32 v3, 0, v2
	v_cndmask_b32_e64 v2, v2, v3, s[26:27]
	v_min_i32_e32 v2, s18, v2
	v_add_u32_e32 v2, s90, v2
	v_mad_i64_i32 v[144:145], s[0:1], v2, s38, v[0:1]
	v_lshl_add_u64 v[2:3], v[144:145], 0, s[40:41]
	v_lshl_add_u64 v[2:3], v[2:3], 0, v[132:133]
	v_lshl_add_u64 v[4:5], v[2:3], 0, s[42:43]
	v_add_co_u32_e32 v2, vcc, s8, v2
	v_cmp_le_i32_e64 s[28:29], s6, v232
	s_nop 0
	v_addc_co_u32_e32 v3, vcc, 0, v3, vcc
	global_load_dwordx4 v[92:95], v[2:3], off offset:2560
	global_load_dwordx4 v[88:91], v[4:5], off offset:16
	global_load_dword v178, v[4:5], off offset:1040
	global_load_dword v179, v[4:5], off offset:2064
	v_max_i32_e32 v2, 0, v232
	v_cndmask_b32_e64 v2, v232, v2, s[26:27]
	v_min_i32_e32 v2, s18, v2
	v_add_u32_e32 v2, s90, v2
	v_mad_i64_i32 v[146:147], s[0:1], v2, s38, v[0:1]
	v_lshl_add_u64 v[2:3], v[146:147], 0, s[40:41]
	v_lshl_add_u64 v[2:3], v[2:3], 0, v[132:133]
	v_lshl_add_u64 v[4:5], v[2:3], 0, s[42:43]
	v_add_co_u32_e32 v2, vcc, 0x3000000, v2
	v_cmp_gt_i32_e64 s[24:25], s6, v232
	s_nop 0
	v_addc_co_u32_e32 v3, vcc, 0, v3, vcc
	global_load_dwordx4 v[52:55], v[2:3], off offset:2560
	global_load_dwordx4 v[48:51], v[4:5], off offset:16
	global_load_dword v180, v[4:5], off offset:1040
	global_load_dword v181, v[4:5], off offset:2064
	v_min_i32_e32 v2, s18, v6
	v_add_u32_e32 v2, s90, v2
	v_mad_i64_i32 v[128:129], s[0:1], v2, s38, v[0:1]
	v_cmp_gt_i32_e32 vcc, 3, v232
	s_and_b64 s[0:1], s[26:27], vcc
	s_lshl_b32 s17, s17, 7
	s_nor_b64 s[92:93], s[0:1], s[28:29]
	v_lshlrev_b32_e32 v132, 1, v234
	s_and_saveexec_b64 s[0:1], s[92:93]
	s_xor_b64 s[90:91], exec, s[0:1]
	s_cbranch_execz .LBB0_207
	s_lshl_b32 s40, s17, 1
	v_lshl_add_u64 v[0:1], v[128:129], 0, s[40:41]
	v_lshl_add_u64 v[0:1], v[0:1], 0, v[132:133]
	v_lshl_add_u64 v[2:3], v[0:1], 0, s[42:43]
	v_add_co_u32_e32 v0, vcc, 0x3000000, v0
	global_load_dwordx4 v[14:17], v[2:3], off offset:16
	s_nop 0
	v_addc_co_u32_e32 v1, vcc, 0, v1, vcc
	global_load_dwordx4 v[18:21], v[0:1], off offset:2560
	s_waitcnt vmcnt(0)
	v_and_b32_e32 v5, 0xffff0000, v14
	v_lshlrev_b32_e32 v4, 16, v14
	v_and_b32_e32 v7, 0xffff0000, v15
	v_lshlrev_b32_e32 v6, 16, v15
	v_and_b32_e32 v1, 0xffff0000, v16
	v_lshlrev_b32_e32 v0, 16, v16
	v_and_b32_e32 v3, 0xffff0000, v17
	v_and_b32_e32 v13, 0xffff0000, v18
	v_lshlrev_b32_e32 v12, 16, v18
	v_and_b32_e32 v15, 0xffff0000, v19
	v_lshlrev_b32_e32 v14, 16, v19
	v_and_b32_e32 v9, 0xffff0000, v20
	v_lshlrev_b32_e32 v8, 16, v20
	v_and_b32_e32 v11, 0xffff0000, v21
	v_lshlrev_b32_e32 v10, 16, v21
	v_lshlrev_b32_e32 v2, 16, v17
